# nsa cmp unit pass 1: per-element validity select replaced by one per-row select on the running max (bit-identical sum), exp overlapped with previous add
# baseline (speedup 1.0000x reference)
; DI int crow(int i, int h) { return (i & 3) + 8 * (i >> 2) + 4 * h; }
; DI void nsa_cmp_unit(const Params& p, int u, char* smem) {
;     ...
;       float mx = -1e30f;
; #pragma unroll
;       for (int i = 0; i < 16; ++i) { const bool valid = (32 * T + crow(i, h)) < nc; const float v = valid ? s[i] : -1e30f; s[i] = v; mx = fmaxf(mx, v); }
;       mx = fmaxf(mx, __shfl_xor(mx, 32));
;       const float mn = fmaxf(m, mx); float ps = 0.f;
; #pragma unroll
;       for (int i = 0; i < 16; ++i) ps += s[i] > -5e29f ? __expf(s[i] - mn) : 0.f;
;       l = l * __expf(m - mn) + ps; m = mn;
;     }
.LBB0_435:
	s_mov_b32 s9, 0xf149f2ca
	v_mov_b32_e32 v56, v140
	s_add_i32 s8, s8, -1
	s_waitcnt lgkmcnt(0)
	v_mfma_f32_32x32x16_bf16 v[34:49], v[234:237], v[102:105], 0
	s_cmp_lg_u32 s8, 0
	v_mfma_f32_32x32x16_bf16 v[34:49], v[238:241], v[98:101], v[34:49]
	v_mfma_f32_32x32x16_bf16 v[34:49], v[242:245], v[106:109], v[34:49]
	v_add_u32_e32 v51, 0x1200, v51
	v_mfma_f32_32x32x16_bf16 v[34:49], v[246:249], v[110:113], v[34:49]
	ds_read_b128 v[234:237], v51
	ds_read_b128 v[238:241], v51 offset:32
	ds_read_b128 v[242:245], v51 offset:64
	ds_read_b128 v[246:249], v51 offset:96
	v_subrev_u32_e32 v52, 27, v50
	v_cmp_lt_i32_e32 vcc, v52, v116
	v_subrev_u32_e32 v52, 26, v50
	v_subrev_u32_e32 v53, 25, v50
	s_nop 7
	v_cndmask_b32_e32 v34, v206, v34, vcc
	v_cmp_lt_i32_e32 vcc, v52, v116
	s_nop 1
	v_cndmask_b32_e32 v35, v206, v35, vcc
	v_cmp_lt_i32_e32 vcc, v53, v116
	v_subrev_u32_e32 v53, 24, v50
	v_max3_f32 v52, v34, s9, v35
	v_cndmask_b32_e32 v36, v206, v36, vcc
	v_cmp_lt_i32_e32 vcc, v53, v116
	v_subrev_u32_e32 v53, 19, v50
	s_nop 0
	v_cndmask_b32_e32 v37, v206, v37, vcc
	v_cmp_lt_i32_e32 vcc, v53, v116
	v_subrev_u32_e32 v53, 18, v50
	v_max3_f32 v52, v52, v36, v37
	v_cndmask_b32_e32 v38, v206, v38, vcc
	v_cmp_lt_i32_e32 vcc, v53, v116
	v_subrev_u32_e32 v53, 17, v50
	s_nop 0
	v_cndmask_b32_e32 v39, v206, v39, vcc
	v_cmp_lt_i32_e32 vcc, v53, v116
	v_add_u32_e32 v53, -16, v50
	v_max3_f32 v52, v52, v38, v39
	v_cndmask_b32_e32 v40, v206, v40, vcc
	v_cmp_lt_i32_e32 vcc, v53, v116
	v_add_u32_e32 v53, -11, v50
	s_nop 0
	v_cndmask_b32_e32 v41, v206, v41, vcc
	v_cmp_lt_i32_e32 vcc, v53, v116
	v_add_u32_e32 v53, -10, v50
	v_max3_f32 v52, v52, v40, v41
	v_cndmask_b32_e32 v42, v206, v42, vcc
	v_cmp_lt_i32_e32 vcc, v53, v116
	v_add_u32_e32 v53, -9, v50
	s_nop 0
	v_cndmask_b32_e32 v43, v206, v43, vcc
	v_cmp_lt_i32_e32 vcc, v53, v116
	v_add_u32_e32 v53, -8, v50
	v_max3_f32 v52, v52, v42, v43
	v_cndmask_b32_e32 v44, v206, v44, vcc
	v_cmp_lt_i32_e32 vcc, v53, v116
	v_add_u32_e32 v53, -3, v50
	s_nop 0
	v_cndmask_b32_e32 v45, v206, v45, vcc
	v_cmp_lt_i32_e32 vcc, v53, v116
	v_add_u32_e32 v53, -2, v50
	v_max3_f32 v52, v52, v44, v45
	v_cndmask_b32_e32 v46, v206, v46, vcc
	v_cmp_lt_i32_e32 vcc, v53, v116
	v_add_u32_e32 v53, -1, v50
	s_nop 0
	v_cndmask_b32_e32 v47, v206, v47, vcc
	v_cmp_lt_i32_e32 vcc, v53, v116
	v_max3_f32 v52, v52, v46, v47
	s_nop 0
	v_cndmask_b32_e32 v48, v206, v48, vcc
	v_cmp_lt_i32_e32 vcc, v50, v116
	v_add_u32_e32 v50, 32, v50
	s_nop 0
	v_cndmask_b32_e32 v49, v206, v49, vcc
	v_max3_f32 v52, v52, v48, v49
	ds_bpermute_b32 v53, v126, v52
	s_waitcnt lgkmcnt(0)
	v_max3_f32 v140, v56, v52, v53
	v_sub_f32_e32 v34, v34, v140
	v_mul_f32_e32 v34, 0x3fb8aa3b, v34
	v_exp_f32_e32 v34, v34
	v_sub_f32_e32 v35, v35, v140
	v_mul_f32_e32 v35, 0x3fb8aa3b, v35
	v_exp_f32_e32 v35, v35
	v_sub_f32_e32 v232, v36, v140
	v_mul_f32_e32 v232, 0x3fb8aa3b, v232
	v_exp_f32_e32 v232, v232
	v_add_f32_e32 v34, v35, v34
	v_sub_f32_e32 v35, v37, v140
	v_mul_f32_e32 v35, 0x3fb8aa3b, v35
	v_exp_f32_e32 v35, v35
	v_add_f32_e32 v34, v232, v34
	v_sub_f32_e32 v232, v38, v140
	v_mul_f32_e32 v232, 0x3fb8aa3b, v232
	v_exp_f32_e32 v232, v232
	v_add_f32_e32 v34, v35, v34
	v_sub_f32_e32 v35, v39, v140
	v_mul_f32_e32 v35, 0x3fb8aa3b, v35
	v_exp_f32_e32 v35, v35
	v_add_f32_e32 v34, v232, v34
	v_sub_f32_e32 v232, v40, v140
	v_mul_f32_e32 v232, 0x3fb8aa3b, v232
	v_exp_f32_e32 v232, v232
	v_add_f32_e32 v34, v35, v34
	v_sub_f32_e32 v35, v41, v140
	v_mul_f32_e32 v35, 0x3fb8aa3b, v35
	v_exp_f32_e32 v35, v35
	v_add_f32_e32 v34, v232, v34
	v_sub_f32_e32 v232, v42, v140
	v_mul_f32_e32 v232, 0x3fb8aa3b, v232
	v_exp_f32_e32 v232, v232
	v_add_f32_e32 v34, v35, v34
	v_sub_f32_e32 v35, v43, v140
	v_mul_f32_e32 v35, 0x3fb8aa3b, v35
	v_exp_f32_e32 v35, v35
	v_add_f32_e32 v34, v232, v34
	v_sub_f32_e32 v232, v44, v140
	v_mul_f32_e32 v232, 0x3fb8aa3b, v232
	v_exp_f32_e32 v232, v232
	v_add_f32_e32 v34, v35, v34
	v_sub_f32_e32 v35, v45, v140
	v_mul_f32_e32 v35, 0x3fb8aa3b, v35
	v_exp_f32_e32 v35, v35
	v_add_f32_e32 v34, v232, v34
	v_sub_f32_e32 v232, v46, v140
	v_mul_f32_e32 v232, 0x3fb8aa3b, v232
	v_exp_f32_e32 v232, v232
	v_add_f32_e32 v34, v35, v34
	v_sub_f32_e32 v35, v47, v140
	v_mul_f32_e32 v35, 0x3fb8aa3b, v35
	v_exp_f32_e32 v35, v35
	v_add_f32_e32 v34, v232, v34
	v_sub_f32_e32 v232, v48, v140
	v_mul_f32_e32 v232, 0x3fb8aa3b, v232
	v_exp_f32_e32 v232, v232
	v_add_f32_e32 v34, v35, v34
	v_sub_f32_e32 v35, v49, v140
	v_mul_f32_e32 v35, 0x3fb8aa3b, v35
	v_exp_f32_e32 v35, v35
	v_add_f32_e32 v34, v232, v34
	v_sub_f32_e32 v232, v56, v140
	v_mul_f32_e32 v232, 0x3fb8aa3b, v232
	v_exp_f32_e32 v232, v232
	v_add_f32_e32 v34, v35, v34
	v_cmp_lt_f32_e32 vcc, s60, v140
	s_nop 1
	v_cndmask_b32_e32 v34, 0, v34, vcc
	v_fma_f32 v0, v0, v232, v34
	s_cbranch_scc1 .LBB0_435
